# v54 + out-phase epilogue: residual-stream X loads hoisted ahead of the last k-step and issued together, counted waits
# speedup vs baseline: 1.0151x; 1.0037x over previous
.LBB0_582:
	s_add_i32 s7, s5, 1
	s_bitcmp1_b32 s5, 0
	s_cselect_b32 s5, 0x9000, 0
	s_add_i32 s5, s5, 0
	v_add_u32_e32 v118, s5, v93
	v_add_u32_e32 v119, v118, v94
	v_add_u32_e32 v156, v118, v95
	ds_read_b128 v[102:105], v119
	ds_read_b128 v[106:109], v119 offset:2048
	ds_read_b128 v[110:113], v119 offset:4096
	ds_read_b128 v[114:117], v119 offset:6144
	ds_read_b128 v[118:121], v119 offset:8192
	ds_read_b128 v[122:125], v156 offset:20480
	ds_read_b128 v[126:129], v156 offset:22528
	ds_read_b128 v[130:133], v156 offset:24576
	ds_read_b128 v[156:159], v156 offset:26624
	v_add_u32_e32 v206, s5, v96
	v_add_u32_e32 v207, v206, v94
	v_add_u32_e32 v208, v206, v95
	ds_read_b128 v[210:213], v207
	ds_read_b128 v[214:217], v207 offset:2048
	ds_read_b128 v[218:221], v207 offset:4096
	ds_read_b128 v[222:225], v207 offset:6144
	ds_read_b128 v[226:229], v207 offset:8192
	ds_read_b128 v[230:233], v208 offset:20480
	ds_read_b128 v[234:237], v208 offset:22528
	ds_read_b128 v[238:241], v208 offset:24576
	ds_read_b128 v[242:245], v208 offset:26624
	s_setprio 1
	s_waitcnt lgkmcnt(9)
	v_mfma_f32_16x16x32_bf16 v[76:79], v[122:125], v[102:105], v[76:79]
	v_mfma_f32_16x16x32_bf16 v[72:75], v[126:129], v[102:105], v[72:75]
	v_mfma_f32_16x16x32_bf16 v[68:71], v[130:133], v[102:105], v[68:71]
	v_mfma_f32_16x16x32_bf16 v[64:67], v[156:159], v[102:105], v[64:67]
	v_mfma_f32_16x16x32_bf16 v[60:63], v[122:125], v[106:109], v[60:63]
	v_mfma_f32_16x16x32_bf16 v[56:59], v[126:129], v[106:109], v[56:59]
	v_mfma_f32_16x16x32_bf16 v[52:55], v[130:133], v[106:109], v[52:55]
	v_mfma_f32_16x16x32_bf16 v[48:51], v[156:159], v[106:109], v[48:51]
	v_mfma_f32_16x16x32_bf16 v[44:47], v[122:125], v[110:113], v[44:47]
	v_mfma_f32_16x16x32_bf16 v[40:43], v[126:129], v[110:113], v[40:43]
	v_mfma_f32_16x16x32_bf16 v[36:39], v[130:133], v[110:113], v[36:39]
	v_mfma_f32_16x16x32_bf16 v[32:35], v[156:159], v[110:113], v[32:35]
	v_mfma_f32_16x16x32_bf16 v[28:31], v[122:125], v[114:117], v[28:31]
	v_mfma_f32_16x16x32_bf16 v[24:27], v[126:129], v[114:117], v[24:27]
	v_mfma_f32_16x16x32_bf16 v[20:23], v[130:133], v[114:117], v[20:23]
	v_mfma_f32_16x16x32_bf16 v[16:19], v[156:159], v[114:117], v[16:19]
	v_mfma_f32_16x16x32_bf16 v[12:15], v[122:125], v[118:121], v[12:15]
	v_mfma_f32_16x16x32_bf16 v[8:11], v[126:129], v[118:121], v[8:11]
	v_mfma_f32_16x16x32_bf16 v[4:7], v[130:133], v[118:121], v[4:7]
	v_mfma_f32_16x16x32_bf16 v[0:3], v[156:159], v[118:121], v[0:3]
	s_setprio 0
	s_setprio 1
	s_waitcnt lgkmcnt(0)
	s_setprio 0
	s_barrier
	s_add_u32 s8, s8, 0x80
	s_addc_u32 s9, s9, 0
	s_mov_b32 s13, s5
	v_add_u32_e32 v190, s13, v92
	v_lshl_add_u64 v[186:187], v[88:89], 0, s[8:9]
	s_mov_b64 s[14:15], 0x1c9b1080
	v_readfirstlane_b32 s13, v190
	v_add_u32_e32 v191, 0x1000, v190
	v_lshl_add_u64 v[188:189], v[186:187], 0, s[14:15]
	s_mov_b32 m0, s13
	s_mov_b64 s[14:15], 0x1c9c1080
	v_readfirstlane_b32 s13, v191
	v_add_u32_e32 v191, 0x2000, v190
	global_load_lds_dwordx4 v[188:189], off
	v_lshl_add_u64 v[188:189], v[186:187], 0, s[14:15]
	s_mov_b32 m0, s13
	s_mov_b64 s[14:15], 0x1c9d1080
	v_readfirstlane_b32 s13, v191
	v_add_u32_e32 v191, 0x3000, v190
	global_load_lds_dwordx4 v[188:189], off
	v_lshl_add_u64 v[188:189], v[186:187], 0, s[14:15]
	s_mov_b32 m0, s13
	s_mov_b64 s[14:15], 0x1c9e1080
	v_readfirstlane_b32 s13, v191
	global_load_lds_dwordx4 v[188:189], off
	v_lshl_add_u64 v[188:189], v[186:187], 0, s[14:15]
	s_mov_b32 m0, s13
	s_mov_b64 s[14:15], 0x1c9f1080
	global_load_lds_dwordx4 v[188:189], off
	v_add_u32_e32 v188, 0x4000, v190
	v_lshl_add_u64 v[186:187], v[186:187], 0, s[14:15]
	v_readfirstlane_b32 s13, v188
	s_mov_b32 m0, s13
	v_add_u32_e32 v191, 0x5000, v190
	global_load_lds_dwordx4 v[186:187], off
	v_lshl_add_u64 v[186:187], v[90:91], 0, s[8:9]
	s_mov_b64 s[14:15], 0x14b31080
	v_readfirstlane_b32 s13, v191
	v_add_u32_e32 v191, 0x6000, v190
	v_lshl_add_u64 v[188:189], v[186:187], 0, s[14:15]
	s_mov_b32 m0, s13
	s_mov_b64 s[14:15], 0x14b41080
	v_readfirstlane_b32 s13, v191
	v_add_u32_e32 v191, 0x7000, v190
	global_load_lds_dwordx4 v[188:189], off
	v_lshl_add_u64 v[188:189], v[186:187], 0, s[14:15]
	s_mov_b32 m0, s13
	s_mov_b64 s[14:15], 0x14b51080
	v_readfirstlane_b32 s13, v191
	global_load_lds_dwordx4 v[188:189], off
	v_lshl_add_u64 v[188:189], v[186:187], 0, s[14:15]
	s_mov_b32 m0, s13
	s_mov_b64 s[14:15], 0x14b61080
	global_load_lds_dwordx4 v[188:189], off
	v_add_u32_e32 v188, 0x8000, v190
	v_lshl_add_u64 v[186:187], v[186:187], 0, s[14:15]
	v_readfirstlane_b32 s13, v188
	s_mov_b32 m0, s13
	s_nop 0
	global_load_lds_dwordx4 v[186:187], off
	s_setprio 1
	v_mfma_f32_16x16x32_bf16 v[76:79], v[230:233], v[210:213], v[76:79]
	v_mfma_f32_16x16x32_bf16 v[72:75], v[234:237], v[210:213], v[72:75]
	v_mfma_f32_16x16x32_bf16 v[68:71], v[238:241], v[210:213], v[68:71]
	v_mfma_f32_16x16x32_bf16 v[64:67], v[242:245], v[210:213], v[64:67]
	v_mfma_f32_16x16x32_bf16 v[60:63], v[230:233], v[214:217], v[60:63]
	v_mfma_f32_16x16x32_bf16 v[56:59], v[234:237], v[214:217], v[56:59]
	v_mfma_f32_16x16x32_bf16 v[52:55], v[238:241], v[214:217], v[52:55]
	v_mfma_f32_16x16x32_bf16 v[48:51], v[242:245], v[214:217], v[48:51]
	v_mfma_f32_16x16x32_bf16 v[44:47], v[230:233], v[218:221], v[44:47]
	v_mfma_f32_16x16x32_bf16 v[40:43], v[234:237], v[218:221], v[40:43]
	v_mfma_f32_16x16x32_bf16 v[36:39], v[238:241], v[218:221], v[36:39]
	v_mfma_f32_16x16x32_bf16 v[32:35], v[242:245], v[218:221], v[32:35]
	v_mfma_f32_16x16x32_bf16 v[28:31], v[230:233], v[222:225], v[28:31]
	v_mfma_f32_16x16x32_bf16 v[24:27], v[234:237], v[222:225], v[24:27]
	v_mfma_f32_16x16x32_bf16 v[20:23], v[238:241], v[222:225], v[20:23]
	v_mfma_f32_16x16x32_bf16 v[16:19], v[242:245], v[222:225], v[16:19]
	v_mfma_f32_16x16x32_bf16 v[12:15], v[230:233], v[226:229], v[12:15]
	v_mfma_f32_16x16x32_bf16 v[8:11], v[234:237], v[226:229], v[8:11]
	v_mfma_f32_16x16x32_bf16 v[4:7], v[238:241], v[226:229], v[4:7]
	v_mfma_f32_16x16x32_bf16 v[0:3], v[242:245], v[226:229], v[0:3]
	s_setprio 0
	s_cmpk_lg_i32 s8, 0x700
	s_mov_b32 s5, s7
	s_waitcnt vmcnt(9)
	s_barrier
	s_cbranch_scc1 .LBB0_582
	s_add_i32 s7, s5, 1
	s_bitcmp1_b32 s5, 0
	s_cselect_b32 s5, 0x9000, 0
	s_add_i32 s5, s5, 0
	v_add_u32_e32 v118, s5, v93
	v_add_u32_e32 v119, v118, v94
	v_add_u32_e32 v156, v118, v95
	ds_read_b128 v[102:105], v119
	ds_read_b128 v[106:109], v119 offset:2048
	ds_read_b128 v[110:113], v119 offset:4096
	ds_read_b128 v[114:117], v119 offset:6144
	ds_read_b128 v[118:121], v119 offset:8192
	ds_read_b128 v[122:125], v156 offset:20480
	ds_read_b128 v[126:129], v156 offset:22528
	ds_read_b128 v[130:133], v156 offset:24576
	ds_read_b128 v[156:159], v156 offset:26624
	v_add_u32_e32 v206, s5, v96
	v_add_u32_e32 v207, v206, v94
	v_add_u32_e32 v208, v206, v95
	ds_read_b128 v[210:213], v207
	ds_read_b128 v[214:217], v207 offset:2048
	ds_read_b128 v[218:221], v207 offset:4096
	ds_read_b128 v[222:225], v207 offset:6144
	ds_read_b128 v[226:229], v207 offset:8192
	ds_read_b128 v[230:233], v208 offset:20480
	ds_read_b128 v[234:237], v208 offset:22528
	ds_read_b128 v[238:241], v208 offset:24576
	ds_read_b128 v[242:245], v208 offset:26624
	s_setprio 1
	s_waitcnt lgkmcnt(9)
	v_mfma_f32_16x16x32_bf16 v[76:79], v[122:125], v[102:105], v[76:79]
	v_mfma_f32_16x16x32_bf16 v[72:75], v[126:129], v[102:105], v[72:75]
	v_mfma_f32_16x16x32_bf16 v[68:71], v[130:133], v[102:105], v[68:71]
	v_mfma_f32_16x16x32_bf16 v[64:67], v[156:159], v[102:105], v[64:67]
	v_mfma_f32_16x16x32_bf16 v[60:63], v[122:125], v[106:109], v[60:63]
	v_mfma_f32_16x16x32_bf16 v[56:59], v[126:129], v[106:109], v[56:59]
	v_mfma_f32_16x16x32_bf16 v[52:55], v[130:133], v[106:109], v[52:55]
	v_mfma_f32_16x16x32_bf16 v[48:51], v[156:159], v[106:109], v[48:51]
	v_mfma_f32_16x16x32_bf16 v[44:47], v[122:125], v[110:113], v[44:47]
	v_mfma_f32_16x16x32_bf16 v[40:43], v[126:129], v[110:113], v[40:43]
	v_mfma_f32_16x16x32_bf16 v[36:39], v[130:133], v[110:113], v[36:39]
	v_mfma_f32_16x16x32_bf16 v[32:35], v[156:159], v[110:113], v[32:35]
	v_mfma_f32_16x16x32_bf16 v[28:31], v[122:125], v[114:117], v[28:31]
	v_mfma_f32_16x16x32_bf16 v[24:27], v[126:129], v[114:117], v[24:27]
	v_mfma_f32_16x16x32_bf16 v[20:23], v[130:133], v[114:117], v[20:23]
	v_mfma_f32_16x16x32_bf16 v[16:19], v[156:159], v[114:117], v[16:19]
	v_mfma_f32_16x16x32_bf16 v[12:15], v[122:125], v[118:121], v[12:15]
	v_mfma_f32_16x16x32_bf16 v[8:11], v[126:129], v[118:121], v[8:11]
	v_mfma_f32_16x16x32_bf16 v[4:7], v[130:133], v[118:121], v[4:7]
	v_mfma_f32_16x16x32_bf16 v[0:3], v[156:159], v[118:121], v[0:3]
	s_setprio 0
	s_setprio 1
	s_waitcnt lgkmcnt(0)
	v_mfma_f32_16x16x32_bf16 v[76:79], v[230:233], v[210:213], v[76:79]
	v_mfma_f32_16x16x32_bf16 v[72:75], v[234:237], v[210:213], v[72:75]
	v_mfma_f32_16x16x32_bf16 v[68:71], v[238:241], v[210:213], v[68:71]
	v_mfma_f32_16x16x32_bf16 v[64:67], v[242:245], v[210:213], v[64:67]
	v_mfma_f32_16x16x32_bf16 v[60:63], v[230:233], v[214:217], v[60:63]
	v_mfma_f32_16x16x32_bf16 v[56:59], v[234:237], v[214:217], v[56:59]
	v_mfma_f32_16x16x32_bf16 v[52:55], v[238:241], v[214:217], v[52:55]
	v_mfma_f32_16x16x32_bf16 v[48:51], v[242:245], v[214:217], v[48:51]
	v_mfma_f32_16x16x32_bf16 v[44:47], v[230:233], v[218:221], v[44:47]
	v_mfma_f32_16x16x32_bf16 v[40:43], v[234:237], v[218:221], v[40:43]
	v_mfma_f32_16x16x32_bf16 v[36:39], v[238:241], v[218:221], v[36:39]
	v_mfma_f32_16x16x32_bf16 v[32:35], v[242:245], v[218:221], v[32:35]
	v_mfma_f32_16x16x32_bf16 v[28:31], v[230:233], v[222:225], v[28:31]
	v_mfma_f32_16x16x32_bf16 v[24:27], v[234:237], v[222:225], v[24:27]
	v_mfma_f32_16x16x32_bf16 v[20:23], v[238:241], v[222:225], v[20:23]
	v_mfma_f32_16x16x32_bf16 v[16:19], v[242:245], v[222:225], v[16:19]
	v_mfma_f32_16x16x32_bf16 v[12:15], v[230:233], v[226:229], v[12:15]
	v_mfma_f32_16x16x32_bf16 v[8:11], v[234:237], v[226:229], v[8:11]
	v_mfma_f32_16x16x32_bf16 v[4:7], v[238:241], v[226:229], v[4:7]
	v_mfma_f32_16x16x32_bf16 v[0:3], v[242:245], v[226:229], v[0:3]
	s_setprio 0
	s_add_u32 s8, s8, 0x80
	s_addc_u32 s9, s9, 0
	s_mov_b32 s5, s7
	s_waitcnt vmcnt(0)
	s_barrier
	v_add_u32_e32 v232, v97, v176
	v_lshrrev_b32_e32 v233, 2, v232
	v_ashrrev_i32_e32 v234, 7, v232
	v_and_b32_e32 v236, 64, v232
	v_and_b32_e32 v233, 12, v233
	v_and_or_b32 v248, v232, 15, s6
	s_movk_i32 s5, 0x50
	s_lshl_b32 s4, s4, 7
	v_mad_u32_u24 v248, v234, s5, v248
	v_or3_b32 v236, v236, v233, s4
	v_ashrrev_i32_e32 v249, 31, v248
	v_lshlrev_b64 v[248:249], 12, v[248:249]
	v_lshl_add_u64 v[248:249], s[0:1], 0, v[248:249]
	v_ashrrev_i32_e32 v237, 31, v236
	v_lshl_add_u64 v[248:249], v[236:237], 2, v[248:249]
	s_mov_b64 s[4:5], 0x10000
	v_lshl_add_u64 v[246:247], v[248:249], 0, s[4:5]
	s_mov_b64 s[4:5], 0x20000
	v_lshl_add_u64 v[244:245], v[248:249], 0, s[4:5]
	s_mov_b64 s[4:5], 0x30000
	v_lshl_add_u64 v[242:243], v[248:249], 0, s[4:5]
	s_mov_b64 s[4:5], 0x40000
	v_lshl_add_u64 v[240:241], v[248:249], 0, s[4:5]
	global_load_dwordx4 v[178:181], v[248:249], off
	global_load_dwordx4 v[182:185], v[248:249], off offset:64
	global_load_dwordx4 v[186:189], v[248:249], off offset:128
	global_load_dwordx4 v[190:193], v[248:249], off offset:192
	global_load_dwordx4 v[194:197], v[246:247], off
	global_load_dwordx4 v[198:201], v[246:247], off offset:64
	global_load_dwordx4 v[206:209], v[246:247], off offset:128
	global_load_dwordx4 v[210:213], v[246:247], off offset:192
	global_load_dwordx4 v[214:217], v[244:245], off
	global_load_dwordx4 v[218:221], v[244:245], off offset:64
	global_load_dwordx4 v[222:225], v[244:245], off offset:128
	global_load_dwordx4 v[226:229], v[244:245], off offset:192
	v_add_u32_e32 v110, v100, v95
	v_add_u32_e32 v130, v100, v94
	ds_read_b128 v[88:91], v110 offset:63488
	ds_read_b128 v[102:105], v110 offset:61440
	ds_read_b128 v[106:109], v110 offset:59392
	ds_read_b128 v[110:113], v110 offset:57344
	ds_read_b128 v[114:117], v130 offset:45056
	ds_read_b128 v[118:121], v130 offset:43008
	ds_read_b128 v[122:125], v130 offset:40960
	ds_read_b128 v[126:129], v130 offset:38912
	ds_read_b128 v[130:133], v130 offset:36864
	s_setprio 1
	s_waitcnt lgkmcnt(0)
	v_mfma_f32_16x16x32_bf16 v[76:79], v[110:113], v[130:133], v[76:79]
	v_mfma_f32_16x16x32_bf16 v[72:75], v[106:109], v[130:133], v[72:75]
	v_mfma_f32_16x16x32_bf16 v[68:71], v[102:105], v[130:133], v[68:71]
	v_mfma_f32_16x16x32_bf16 v[64:67], v[88:91], v[130:133], v[64:67]
	v_mfma_f32_16x16x32_bf16 v[60:63], v[110:113], v[126:129], v[60:63]
	v_mfma_f32_16x16x32_bf16 v[56:59], v[106:109], v[126:129], v[56:59]
	v_mfma_f32_16x16x32_bf16 v[52:55], v[102:105], v[126:129], v[52:55]
	v_mfma_f32_16x16x32_bf16 v[48:51], v[88:91], v[126:129], v[48:51]
	v_mfma_f32_16x16x32_bf16 v[44:47], v[110:113], v[122:125], v[44:47]
	v_mfma_f32_16x16x32_bf16 v[40:43], v[106:109], v[122:125], v[40:43]
	v_mfma_f32_16x16x32_bf16 v[36:39], v[102:105], v[122:125], v[36:39]
	v_mfma_f32_16x16x32_bf16 v[32:35], v[88:91], v[122:125], v[32:35]
	v_mfma_f32_16x16x32_bf16 v[28:31], v[110:113], v[118:121], v[28:31]
	v_mfma_f32_16x16x32_bf16 v[24:27], v[106:109], v[118:121], v[24:27]
	v_mfma_f32_16x16x32_bf16 v[20:23], v[102:105], v[118:121], v[20:23]
	v_mfma_f32_16x16x32_bf16 v[16:19], v[88:91], v[118:121], v[16:19]
	v_mfma_f32_16x16x32_bf16 v[12:15], v[110:113], v[114:117], v[12:15]
	v_mfma_f32_16x16x32_bf16 v[8:11], v[106:109], v[114:117], v[8:11]
	v_mfma_f32_16x16x32_bf16 v[4:7], v[102:105], v[114:117], v[4:7]
	v_mfma_f32_16x16x32_bf16 v[0:3], v[88:91], v[114:117], v[0:3]
	s_setprio 0
	v_add_u32_e32 v114, v101, v94
	v_add_u32_e32 v130, v101, v95
	ds_read_b128 v[88:91], v114 offset:36864
	ds_read_b128 v[102:105], v114 offset:38912
	ds_read_b128 v[106:109], v114 offset:40960
	ds_read_b128 v[110:113], v114 offset:43008
	ds_read_b128 v[114:117], v114 offset:45056
	ds_read_b128 v[118:121], v130 offset:57344
	ds_read_b128 v[122:125], v130 offset:59392
	ds_read_b128 v[126:129], v130 offset:61440
	ds_read_b128 v[130:133], v130 offset:63488
	s_setprio 1
	s_waitcnt lgkmcnt(3)
	v_mfma_f32_16x16x32_bf16 v[76:79], v[118:121], v[88:91], v[76:79]
	s_waitcnt lgkmcnt(2)
	v_mfma_f32_16x16x32_bf16 v[72:75], v[122:125], v[88:91], v[72:75]
	s_waitcnt lgkmcnt(1)
	v_mfma_f32_16x16x32_bf16 v[68:71], v[126:129], v[88:91], v[68:71]
	s_waitcnt lgkmcnt(0)
	v_mfma_f32_16x16x32_bf16 v[64:67], v[130:133], v[88:91], v[64:67]
	v_mfma_f32_16x16x32_bf16 v[60:63], v[118:121], v[102:105], v[60:63]
	v_mfma_f32_16x16x32_bf16 v[56:59], v[122:125], v[102:105], v[56:59]
	v_mfma_f32_16x16x32_bf16 v[88:91], v[126:129], v[102:105], v[52:55]
	v_mfma_f32_16x16x32_bf16 v[48:51], v[130:133], v[102:105], v[48:51]
	v_mfma_f32_16x16x32_bf16 v[44:47], v[118:121], v[106:109], v[44:47]
	v_mfma_f32_16x16x32_bf16 v[40:43], v[122:125], v[106:109], v[40:43]
	v_mfma_f32_16x16x32_bf16 v[36:39], v[126:129], v[106:109], v[36:39]
	v_mfma_f32_16x16x32_bf16 v[32:35], v[130:133], v[106:109], v[32:35]
	v_mfma_f32_16x16x32_bf16 v[28:31], v[118:121], v[110:113], v[28:31]
	v_mfma_f32_16x16x32_bf16 v[24:27], v[122:125], v[110:113], v[24:27]
	v_mfma_f32_16x16x32_bf16 v[20:23], v[126:129], v[110:113], v[20:23]
	v_mfma_f32_16x16x32_bf16 v[16:19], v[130:133], v[110:113], v[16:19]
	v_mfma_f32_16x16x32_bf16 v[12:15], v[118:121], v[114:117], v[12:15]
	v_mfma_f32_16x16x32_bf16 v[8:11], v[122:125], v[114:117], v[8:11]
	v_mfma_f32_16x16x32_bf16 v[4:7], v[126:129], v[114:117], v[4:7]
	v_mfma_f32_16x16x32_bf16 v[0:3], v[130:133], v[114:117], v[0:3]
	s_setprio 0
	global_load_dwordx4 v[102:105], v[242:243], off
	global_load_dwordx4 v[106:109], v[242:243], off offset:64
	global_load_dwordx4 v[110:113], v[242:243], off offset:128
	global_load_dwordx4 v[114:117], v[242:243], off offset:192
	global_load_dwordx4 v[118:121], v[240:241], off
	global_load_dwordx4 v[122:125], v[240:241], off offset:64
	global_load_dwordx4 v[126:129], v[240:241], off offset:128
	global_load_dwordx4 v[130:133], v[240:241], off offset:192
	s_barrier
	s_mov_b32 s8, 0
	s_waitcnt vmcnt(19)
	v_pk_add_f32 v[76:77], v[76:77], v[178:179]
	v_pk_add_f32 v[78:79], v[78:79], v[180:181]
	global_store_dwordx4 v[248:249], v[76:79], off
	s_waitcnt vmcnt(19)
	v_pk_add_f32 v[72:73], v[72:73], v[182:183]
	v_pk_add_f32 v[74:75], v[74:75], v[184:185]
	global_store_dwordx4 v[248:249], v[72:75], off offset:64
	s_waitcnt vmcnt(19)
	v_pk_add_f32 v[68:69], v[68:69], v[186:187]
	v_pk_add_f32 v[70:71], v[70:71], v[188:189]
	global_store_dwordx4 v[248:249], v[68:71], off offset:128
	s_waitcnt vmcnt(19)
	v_pk_add_f32 v[64:65], v[64:65], v[190:191]
	v_pk_add_f32 v[66:67], v[66:67], v[192:193]
	global_store_dwordx4 v[248:249], v[64:67], off offset:192
	s_waitcnt vmcnt(19)
	v_pk_add_f32 v[60:61], v[60:61], v[194:195]
	v_pk_add_f32 v[62:63], v[62:63], v[196:197]
	global_store_dwordx4 v[246:247], v[60:63], off
	s_waitcnt vmcnt(19)
	v_pk_add_f32 v[56:57], v[56:57], v[198:199]
	v_pk_add_f32 v[58:59], v[58:59], v[200:201]
	global_store_dwordx4 v[246:247], v[56:59], off offset:64
	s_waitcnt vmcnt(19)
	v_pk_add_f32 v[88:89], v[88:89], v[206:207]
	v_pk_add_f32 v[90:91], v[90:91], v[208:209]
	global_store_dwordx4 v[246:247], v[88:91], off offset:128
	s_waitcnt vmcnt(19)
	v_pk_add_f32 v[48:49], v[48:49], v[210:211]
	v_pk_add_f32 v[50:51], v[50:51], v[212:213]
	global_store_dwordx4 v[246:247], v[48:51], off offset:192
	s_waitcnt vmcnt(19)
	v_pk_add_f32 v[44:45], v[44:45], v[214:215]
	v_pk_add_f32 v[46:47], v[46:47], v[216:217]
	global_store_dwordx4 v[244:245], v[44:47], off
	s_waitcnt vmcnt(19)
	v_pk_add_f32 v[40:41], v[40:41], v[218:219]
	v_pk_add_f32 v[42:43], v[42:43], v[220:221]
	global_store_dwordx4 v[244:245], v[40:43], off offset:64
	s_waitcnt vmcnt(19)
	v_pk_add_f32 v[36:37], v[36:37], v[222:223]
	v_pk_add_f32 v[38:39], v[38:39], v[224:225]
	global_store_dwordx4 v[244:245], v[36:39], off offset:128
	s_waitcnt vmcnt(19)
	v_pk_add_f32 v[32:33], v[32:33], v[226:227]
	v_pk_add_f32 v[34:35], v[34:35], v[228:229]
	global_store_dwordx4 v[244:245], v[32:35], off offset:192
	s_waitcnt vmcnt(19)
	v_pk_add_f32 v[28:29], v[28:29], v[102:103]
	v_pk_add_f32 v[30:31], v[30:31], v[104:105]
	global_store_dwordx4 v[242:243], v[28:31], off
	s_waitcnt vmcnt(19)
	v_pk_add_f32 v[24:25], v[24:25], v[106:107]
	v_pk_add_f32 v[26:27], v[26:27], v[108:109]
	global_store_dwordx4 v[242:243], v[24:27], off offset:64
	s_waitcnt vmcnt(19)
	v_pk_add_f32 v[20:21], v[20:21], v[110:111]
	v_pk_add_f32 v[22:23], v[22:23], v[112:113]
	global_store_dwordx4 v[242:243], v[20:23], off offset:128
	s_waitcnt vmcnt(19)
	v_pk_add_f32 v[16:17], v[16:17], v[114:115]
	v_pk_add_f32 v[18:19], v[18:19], v[116:117]
	global_store_dwordx4 v[242:243], v[16:19], off offset:192
	s_waitcnt vmcnt(19)
	v_pk_add_f32 v[12:13], v[12:13], v[118:119]
	v_pk_add_f32 v[14:15], v[14:15], v[120:121]
	global_store_dwordx4 v[240:241], v[12:15], off
	s_waitcnt vmcnt(19)
	v_pk_add_f32 v[8:9], v[8:9], v[122:123]
	v_pk_add_f32 v[10:11], v[10:11], v[124:125]
	global_store_dwordx4 v[240:241], v[8:11], off offset:64
	s_waitcnt vmcnt(19)
	v_pk_add_f32 v[4:5], v[4:5], v[126:127]
	v_pk_add_f32 v[6:7], v[6:7], v[128:129]
	global_store_dwordx4 v[240:241], v[4:7], off offset:128
	s_waitcnt vmcnt(19)
	v_pk_add_f32 v[0:1], v[0:1], v[130:131]
	v_pk_add_f32 v[2:3], v[2:3], v[132:133]
	global_store_dwordx4 v[240:241], v[0:3], off offset:192
